# attention work queue: next-item atomic issued at item start without wait, published to LDS by wave 0 at item end behind one barrier; loop head reads the item word with ds_read (no vmcnt(0) at item bou
# baseline (speedup 1.0000x reference)
; __global__ void __launch_bounds__(512, 2) mega(Params p) {
;     ...
;       for (int par = 0;; par ^= 1) {
;         const int item = __builtin_amdgcn_readfirstlane(s_item[par]);
;         if (item >= total) break;
;         if (tid == 0) s_item[par ^ 1] = atomicAdd(&CTR[layer], 1);
.LBB0_1239:
	s_xor_b32 s25, s25, 1
	v_cmp_gt_u32_e32 vcc, 64, v179
	s_cbranch_vccz .Lq_pub_skip
	s_waitcnt vmcnt(4)
	v_readfirstlane_b32 s0, v241
	v_mov_b32_e32 v243, s25
	v_lshlrev_b32_e32 v243, 2, v243
	v_add_u32_e32 v243, 0x24a00, v243
	v_mov_b32_e32 v242, s0
	ds_write_b32 v243, v242
	s_waitcnt lgkmcnt(0)
.Lq_pub_skip:
	s_barrier
	s_mov_b64 s[0:1], 0

; __global__ void __launch_bounds__(512, 2) mega(Params p) {
;     ...
;         if (tid == 0) s_item[par ^ 1] = atomicAdd(&CTR[layer], 1);
.LBB0_1245:
	s_mov_b64 s[10:11], exec
	v_mbcnt_lo_u32_b32 v0, s10, 0
	v_mbcnt_hi_u32_b32 v0, s11, v0
	v_cmp_eq_u32_e32 vcc, 0, v0
	s_and_saveexec_b64 s[8:9], vcc
	s_cbranch_execz .LBB0_1247
	s_bcnt1_i32_b64 s10, s[10:11]
	v_mov_b32_e32 v241, s10
	global_atomic_add v241, v1, v241, s[78:79] sc0
.LBB0_1247:
	s_or_b64 exec, exec, s[8:9]
	s_or_b64 exec, exec, s[0:1]
	s_cmp_ge_i32 s26, s22
	s_mov_b64 s[0:1], -1
	s_cbranch_scc0 .LBB0_1244
